# v21 + FFN-up epilogue no longer drains the next tile's prefetch LDS-DMA (vmcnt(0) dropped; conv weights are older loads already retired by the K-loop's counted waits)
# baseline (speedup 1.0000x reference)
.LBB0_1165:
	s_or_b64 exec, exec, s[34:35]
	s_nop 0
	v_mul_f32_e32 v238, s101, v238
	v_mul_f32_e32 v239, s101, v239
	ds_write2st64_b32 v217, v238, v239 offset1:8
	s_waitcnt lgkmcnt(0)
	s_barrier
	v_or_b32_e32 v188, s2, v193
	v_ashrrev_i32_e32 v189, 31, v188
	s_and_saveexec_b64 s[2:3], s[96:97]
	s_xor_b64 s[34:35], exec, s[2:3]
	s_andn2_saveexec_b64 s[34:35], s[34:35]
	s_cbranch_execz .LBB0_1167
	s_ashr_i32 s23, s22, 31
	v_readlane_b32 s60, v252, 48
	s_lshl_b64 s[2:3], s[22:23], 2
	v_cndmask_b32_e64 v130, 2, 0, s[46:47]
	v_readlane_b32 s61, v252, 49
	v_or_b32_e32 v132, s2, v130
	s_mov_b32 s2, 0xb000
	v_mov_b64_e32 v[130:131], s[60:61]
	v_mad_u64_u32 v[130:131], s[60:61], v132, s2, v[130:131]
	v_mov_b32_e32 v132, 0xb000
	v_mad_i32_i24 v131, s3, v132, v131
	v_lshl_add_u64 v[134:135], v[188:189], 2, v[130:131]
	v_cndmask_b32_e64 v133, v87, v129, s[46:47]
	v_cndmask_b32_e64 v132, v86, v128, s[46:47]
	v_cndmask_b32_e64 v131, v85, v127, s[46:47]
	v_cndmask_b32_e64 v130, v84, v126, s[46:47]
	v_add_co_u32_e32 v136, vcc, s2, v134
	global_store_dwordx4 v[134:135], v[130:133], off
	s_nop 0
	v_addc_co_u32_e32 v137, vcc, 0, v135, vcc
	v_cndmask_b32_e64 v133, v83, v125, s[46:47]
	v_cndmask_b32_e64 v132, v82, v124, s[46:47]
	v_cndmask_b32_e64 v131, v81, v123, s[46:47]
	v_cndmask_b32_e64 v130, v80, v122, s[46:47]
	global_store_dwordx4 v[136:137], v[130:133], off
	s_movk_i32 s2, 0x5000
	s_nop 0
	v_cndmask_b32_e64 v133, v19, v59, s[46:47]
	v_cndmask_b32_e64 v132, v18, v58, s[46:47]
	v_cndmask_b32_e64 v131, v17, v57, s[46:47]
	v_cndmask_b32_e64 v130, v16, v56, s[46:47]
	global_store_dwordx4 v[134:135], v[130:133], off offset:16
	s_nop 1
	v_cndmask_b32_e64 v133, v23, v55, s[46:47]
	v_cndmask_b32_e64 v132, v22, v54, s[46:47]
	v_cndmask_b32_e64 v131, v21, v53, s[46:47]
	v_cndmask_b32_e64 v130, v20, v52, s[46:47]
	global_store_dwordx4 v[136:137], v[130:133], off offset:16
	v_add_co_u32_e32 v136, vcc, s2, v134
	s_mov_b32 s2, 0x10000
	s_nop 0
	v_addc_co_u32_e32 v137, vcc, 0, v135, vcc
	v_cndmask_b32_e64 v133, v71, v113, s[46:47]
	v_cndmask_b32_e64 v132, v70, v112, s[46:47]
	v_cndmask_b32_e64 v131, v69, v111, s[46:47]
	v_cndmask_b32_e64 v130, v68, v110, s[46:47]
	v_add_co_u32_e32 v134, vcc, s2, v134
	global_store_dwordx4 v[136:137], v[130:133], off offset:2048
	s_nop 0
	v_addc_co_u32_e32 v135, vcc, 0, v135, vcc
	v_cndmask_b32_e64 v133, v67, v109, s[46:47]
	v_cndmask_b32_e64 v132, v66, v108, s[46:47]
	v_cndmask_b32_e64 v131, v65, v107, s[46:47]
	v_cndmask_b32_e64 v130, v64, v106, s[46:47]
	global_store_dwordx4 v[134:135], v[130:133], off offset:2048
	s_nop 1
	v_cndmask_b32_e64 v133, v3, v43, s[46:47]
	v_cndmask_b32_e64 v132, v2, v42, s[46:47]
	v_cndmask_b32_e64 v131, v1, v41, s[46:47]
	v_cndmask_b32_e64 v130, v0, v40, s[46:47]
	global_store_dwordx4 v[136:137], v[130:133], off offset:2064
	s_nop 1
	v_cndmask_b32_e64 v133, v7, v39, s[46:47]
	v_cndmask_b32_e64 v132, v6, v38, s[46:47]
	v_cndmask_b32_e64 v131, v5, v37, s[46:47]
	v_cndmask_b32_e64 v130, v4, v36, s[46:47]
	global_store_dwordx4 v[134:135], v[130:133], off offset:2064
